# v17 plus branchless header for the rotated w_in GEMM loop (one taken branch per iteration instead of two)
# baseline (speedup 1.0000x reference)
; template <class Epi>
; __device__ __forceinline__ void gemm_phase(LAS unsigned char* lds, const Gemm g, const StaticOrder& S, const Epi& E) {
;     ...
;             const bool last = (t == nt - 2);
;             const char* a1 = cA + (size_t)(t + 1) * kstepA;
;             const char* a2 = last ? nA : cA + (size_t)(t + 2) * kstepA; const char* b2 = last ? nB : cB + (size_t)(t + 2) * kstepB;
.LBB0_564:
	s_cmp_eq_u32 s1, 28
	s_cselect_b64 s[22:23], -1, 0
	s_cselect_b64 s[20:21], s[14:15], s[16:17]
	s_and_b64 vcc, exec, s[22:23]
	s_branch .LBB0_563
	s_nop 0
	s_nop 0
